# speedup vs baseline: 1.0024x; 1.0023x over previous
; __device__ __forceinline__ float ex2(float x) { return __builtin_amdgcn_exp2f(x); }
; __device__ __forceinline__ void sb_group(const unsigned char* st, int kgp, int fo, const bf16x8 (&qf)[2][2], f32x4 (&o)[2][4], float (&R)[2],
;                                          float c2, int d0, bool masked) {
;     ...
;         float suf[8];
;         suf[7] = 0.f;
; #pragma unroll
;         for (int j = 6; j >= 0; --j) suf[j] = suf[j + 1] + l1[j + 1];
;         const float tot = suf[0] + l1[0];
;         const float t1 = __shfl_down(tot, 16), t2 = __shfl_down(tot, 32), t3 = __shfl_down(tot, 48);
;         const float E = (kg < 3 ? t1 : 0.f) + (kg < 2 ? t2 : 0.f) + (kg < 1 ? t3 : 0.f);
;         float G = tot + __shfl_xor(tot, 16);
;         G += __shfl_xor(G, 32);
;         const float base = R[qt] + E;
;         float a[8];
; #pragma unroll
;         for (int j = 0; j < 8; ++j) a[j] = ex2(lb[j] + base + suf[j]);
;         R[qt] += G;
; __device__ void attn_b_item(const Params& p, int layer, int b, int h, int qblk, unsigned char* smem) {
;     ...
;                 sb_group(st, kk, fo, qf, o, R, c2, d0, g == gmax);
;                 done = __all(R[0] < RSTOP && R[1] < RSTOP);
.LBB0_412:
	s_or_b64 exec, exec, s[26:27]
	v_add_f32_e32 v89, 0, v89
	v_add_f32_e32 v88, v88, v89
	v_add_f32_e32 v87, v87, v88
	v_add_f32_e32 v86, v86, v87
	v_add_f32_e32 v85, v85, v86
	v_add_f32_e32 v84, v84, v85
	v_add_f32_e32 v83, v83, v84
	v_add_f32_e32 v82, v82, v83
	v_mov_b32_e32 v104, v82
	v_mov_b32_e32 v105, v82
	s_waitcnt lgkmcnt(0)
	s_nop 0
	v_permlane16_swap_b32_e32 v104, v105
	v_add_f32_e32 v106, v104, v105
	v_cndmask_b32_e64 v105, 0, v105, s[2:3]
	v_mov_b32_e32 v135, v106
	v_mov_b32_e32 v136, v106
	s_nop 1
	v_permlane32_swap_b32_e32 v135, v136
	v_cndmask_b32_e64 v104, 0, v136, s[4:5]
	v_add_f32_e32 v104, v105, v104
	v_add_f32_e32 v139, v135, v136
	v_add_f32_e32 v104, v123, v104
	v_add_f32_e32 v76, v76, v104
	v_add_f32_e32 v2, v2, v104
	v_add_f32_e32 v76, v85, v76
	v_add_f32_e32 v2, v2, v83
	v_exp_f32_e32 v83, v76
	v_add_f32_e32 v76, v77, v104
	v_add_f32_e32 v76, v86, v76
	v_exp_f32_e32 v77, v76
	v_add_f32_e32 v76, v78, v104
	v_add_f32_e32 v76, v87, v76
	v_add_f32_e32 v3, v3, v104
	v_exp_f32_e32 v78, v76
	v_add_f32_e32 v76, v79, v104
	v_add_f32_e32 v3, v84, v3
	v_add_f32_e32 v76, v88, v76
	v_exp_f32_e32 v2, v2
	v_exp_f32_e32 v3, v3
	v_exp_f32_e32 v79, v76
	v_add_f32_e32 v76, v80, v104
	v_add_f32_e32 v76, v89, v76
	v_exp_f32_e32 v80, v76
	v_add_f32_e32 v76, v81, v104
	v_add_f32_e32 v76, 0, v76
	v_exp_f32_e32 v81, v76
	v_cvt_pk_bf16_f32 v76, v2, v3
	v_cvt_pk_bf16_f32 v77, v83, v77
	v_cvt_pk_bf16_f32 v78, v78, v79
	v_cvt_pk_bf16_f32 v79, v80, v81
	s_waitcnt lgkmcnt(0)
	v_mfma_f32_16x16x32_bf16 v[12:15], v[68:71], v[76:79], v[12:15]
	v_mov_b32_e32 v68, v138
	v_add_f32_e32 v122, v122, v68
	v_cmp_gt_f32_e32 vcc, s80, v122
	s_waitcnt lgkmcnt(0)
	v_mov_b32_e32 v2, v139
	v_add_f32_e32 v123, v123, v2
	v_cmp_gt_f32_e64 s[2:3], s80, v123
	s_and_b64 s[2:3], vcc, s[2:3]
	v_mfma_f32_16x16x32_bf16 v[16:19], v[72:75], v[76:79], v[16:19]
	v_cndmask_b32_e64 v2, 0, 1, s[2:3]
	v_cmp_ne_u32_e32 vcc, 0, v2
	s_cmp_eq_u64 vcc, exec
	s_cselect_b64 s[2:3], -1, 0
	s_andn2_b64 s[4:5], s[22:23], exec
	s_and_b64 s[2:3], s[2:3], exec
	v_mfma_f32_16x16x32_bf16 v[8:11], v[64:67], v[76:79], v[8:11]
	s_or_b64 s[22:23], s[4:5], s[2:3]
	v_mfma_f32_16x16x32_bf16 v[4:7], v[60:63], v[76:79], v[4:7]

; __device__ __forceinline__ f32x4 mfma16(bf16x8 a, bf16x8 b, f32x4 c) { return __builtin_amdgcn_mfma_f32_16x16x32_bf16(a, b, c, 0, 0, 0); }
; __device__ __forceinline__ float ex2(float x) { return __builtin_amdgcn_exp2f(x); }
; __device__ __forceinline__ float lg2(float x) { return __builtin_amdgcn_logf(x); }
; __device__ __forceinline__ void sb_group(const unsigned char* st, int kgp, int fo, const bf16x8 (&qf)[2][2], f32x4 (&o)[2][4], float (&R)[2],
;                                          float c2, int d0, bool masked) {
;     ...
;         for (int t = 0; t < 2; ++t) s[t] = mfma16(kf[t][1], qf[1][qt], mfma16(kf[t][0], qf[0][qt], zero));
;         float lb[8], l1[8];
; #pragma unroll
;         for (int j = 0; j < 8; ++j) {
;             const float z2 = s[j >> 2][j & 3] * c2;
;             const float sp = lg2(1.f + ex2(-fabsf(z2)));
;             lb[j] = fminf(z2, 0.f) - sp;
;             l1[j] = lb[j] - z2;
;         }
;         if (masked) {
; #pragma unroll
;             for (int j = 0; j < 8; ++j) if (dq - j <= 0) { lb[j] = -INFINITY; l1[j] = 0.f; }
;         }
;         float suf[8];
;         suf[7] = 0.f;
; #pragma unroll
;         for (int j = 6; j >= 0; --j) suf[j] = suf[j + 1] + l1[j + 1];
;         const float tot = suf[0] + l1[0];
;         const float t1 = __shfl_down(tot, 16), t2 = __shfl_down(tot, 32), t3 = __shfl_down(tot, 48);
;         const float E = (kg < 3 ? t1 : 0.f) + (kg < 2 ? t2 : 0.f) + (kg < 1 ? t3 : 0.f);
;         float G = tot + __shfl_xor(tot, 16);
;         G += __shfl_xor(G, 32);
;         const float base = R[qt] + E;
;         float a[8];
; #pragma unroll
;         for (int j = 0; j < 8; ++j) a[j] = ex2(lb[j] + base + suf[j]);
;         R[qt] += G;
.LBB0_417:
	s_or_b64 exec, exec, s[18:19]
	v_add_f32_e32 v115, 0, v115
	v_add_f32_e32 v114, v114, v115
	v_add_f32_e32 v113, v113, v114
	v_add_f32_e32 v112, v112, v113
	v_and_b32_e32 v130, 63, v208
	v_add_f32_e32 v111, v111, v112
	v_cmp_gt_u32_e64 s[2:3], 48, v130
	v_add_f32_e32 v110, v110, v111
	v_bfe_u32 v129, v127, 4, 2
	v_cndmask_b32_e64 v127, 0, 16, s[2:3]
	v_cmp_gt_u32_e64 s[2:3], 16, v130
	v_add_f32_e32 v109, v109, v110
	v_add_lshl_u32 v127, v127, v208, 2
	v_lshl_or_b32 v128, v208, 2, v212
	v_cndmask_b32_e64 v130, 0, 48, s[2:3]
	v_add_f32_e32 v131, v108, v109
	v_and_b32_e32 v134, 1, v129
	v_mov_b32_e32 v132, v131
	v_mov_b32_e32 v133, v131
	v_cmp_eq_u32_e64 s[2:3], 0, v134
	v_cmp_gt_u32_e64 s[4:5], 2, v129
	s_waitcnt lgkmcnt(0)
	v_permlane16_swap_b32_e32 v132, v133
	v_add_f32_e32 v130, v132, v133
	v_cndmask_b32_e64 v133, 0, v133, s[2:3]
	v_mov_b32_e32 v135, v130
	v_mov_b32_e32 v136, v130
	s_nop 1
	v_permlane32_swap_b32_e32 v135, v136
	v_cndmask_b32_e64 v132, 0, v136, s[4:5]
	v_add_f32_e32 v129, v133, v132
	v_add_f32_e32 v138, v135, v136
	v_add_f32_e32 v129, v122, v129
	v_add_f32_e32 v102, v102, v129
	v_add_f32_e32 v2, v2, v129
	v_add_f32_e32 v102, v111, v102
	v_add_f32_e32 v2, v2, v109
	v_exp_f32_e32 v109, v102
	v_add_f32_e32 v102, v103, v129
	v_add_f32_e32 v102, v112, v102
	v_exp_f32_e32 v103, v102
	v_add_f32_e32 v102, v104, v129
	v_add_f32_e32 v102, v113, v102
	v_exp_f32_e32 v104, v102
	v_add_f32_e32 v102, v105, v129
	v_add_f32_e32 v102, v114, v102
	v_exp_f32_e32 v105, v102
	v_add_f32_e32 v102, v106, v129
	v_add_f32_e32 v102, v115, v102
	v_add_f32_e32 v3, v3, v129
	v_exp_f32_e32 v106, v102
	v_add_f32_e32 v102, v107, v129
	v_add_f32_e32 v3, v110, v3
	v_add_f32_e32 v102, 0, v102
	v_exp_f32_e32 v2, v2
	v_exp_f32_e32 v3, v3
	v_exp_f32_e32 v107, v102
	v_cvt_pk_bf16_f32 v103, v109, v103
	v_cvt_pk_bf16_f32 v104, v104, v105
	v_cvt_pk_bf16_f32 v102, v2, v3
	v_cvt_pk_bf16_f32 v105, v106, v107
	v_and_b32_e32 v3, 64, v208
	v_xor_b32_e32 v2, 16, v208
	v_mfma_f32_16x16x32_bf16 v[32:35], v[72:75], v[102:105], v[32:35]
	v_add_u32_e32 v3, 64, v3
	v_cmp_lt_i32_e64 s[8:9], v2, v3
	v_mfma_f32_16x16x32_bf16 v[28:31], v[68:71], v[102:105], v[28:31]
	s_nop 0
	v_cndmask_b32_e64 v2, v208, v2, s[8:9]
	v_mfma_f32_16x16x32_bf16 v[24:27], v[64:67], v[102:105], v[24:27]
	v_mfma_f32_16x16x32_bf16 v[20:23], v[60:63], v[102:105], v[20:23]
	s_waitcnt vmcnt(3)
	v_mfma_f32_16x16x32_bf16 v[102:105], v[88:91], v[44:47], 0
	v_lshlrev_b32_e32 v90, 2, v2
	v_xor_b32_e32 v2, 32, v208
	s_waitcnt vmcnt(2)
	v_mfma_f32_16x16x32_bf16 v[84:87], v[84:87], v[48:51], v[102:105]
	v_cmp_lt_i32_e64 s[8:9], v2, v3
	v_mfma_f32_16x16x32_bf16 v[80:83], v[80:83], v[44:47], 0
	s_nop 0
	v_cndmask_b32_e64 v2, v208, v2, s[8:9]
	v_lshlrev_b32_e32 v91, 2, v2
	s_nop 2
	v_pk_mul_f32 v[2:3], v[84:85], s[60:61] op_sel_hi:[1,0]
	s_waitcnt lgkmcnt(0)
	v_exp_f32_e64 v88, -|v2|
	v_mfma_f32_16x16x32_bf16 v[104:107], v[76:79], v[48:51], v[80:83]
	v_exp_f32_e64 v77, -|v3|
	v_min_f32_e32 v2, 0, v2
	v_add_f32_e32 v76, 1.0, v88
	v_log_f32_e32 v76, v76
	v_add_f32_e32 v77, 1.0, v77
	v_log_f32_e32 v77, v77
	v_pk_mul_f32 v[78:79], v[86:87], s[60:61] op_sel_hi:[1,0]
	v_min_f32_e32 v3, 0, v3
	v_exp_f32_e64 v80, -|v78|
	v_pk_add_f32 v[2:3], v[2:3], v[76:77] neg_lo:[0,1] neg_hi:[0,1]
	v_exp_f32_e64 v77, -|v79|
	v_min_f32_e32 v78, 0, v78
	v_add_f32_e32 v76, 1.0, v80
	v_pk_mul_f32 v[80:81], v[104:105], s[60:61] op_sel_hi:[1,0]
	v_add_f32_e32 v77, 1.0, v77
	v_log_f32_e32 v76, v76
	v_log_f32_e32 v77, v77
	v_exp_f32_e64 v82, -|v80|
	v_min_f32_e32 v79, 0, v79
	v_pk_add_f32 v[76:77], v[78:79], v[76:77] neg_lo:[0,1] neg_hi:[0,1]
	v_exp_f32_e64 v79, -|v81|
	v_add_f32_e32 v78, 1.0, v82
	v_pk_mul_f32 v[82:83], v[106:107], s[60:61] op_sel_hi:[1,0]
	v_log_f32_e32 v78, v78
	v_exp_f32_e64 v88, -|v82|
	v_exp_f32_e64 v89, -|v83|
	v_add_f32_e32 v79, 1.0, v79
	v_log_f32_e32 v79, v79
	v_add_f32_e32 v88, 1.0, v88
	v_add_f32_e32 v89, 1.0, v89
	v_log_f32_e32 v88, v88
	v_log_f32_e32 v89, v89
	v_min_f32_e32 v80, 0, v80
	v_min_f32_e32 v81, 0, v81
	v_pk_add_f32 v[78:79], v[80:81], v[78:79] neg_lo:[0,1] neg_hi:[0,1]
	v_min_f32_e32 v80, 0, v82
	v_min_f32_e32 v81, 0, v83
	v_pk_add_f32 v[80:81], v[80:81], v[88:89] neg_lo:[0,1] neg_hi:[0,1]
	v_pk_fma_f32 v[82:83], v[84:85], s[60:61], v[2:3] op_sel_hi:[1,0,1] neg_lo:[1,0,0] neg_hi:[1,0,0]
	v_pk_fma_f32 v[84:85], v[86:87], s[60:61], v[76:77] op_sel_hi:[1,0,1] neg_lo:[1,0,0] neg_hi:[1,0,0]
	v_pk_fma_f32 v[86:87], v[104:105], s[60:61], v[78:79] op_sel_hi:[1,0,1] neg_lo:[1,0,0] neg_hi:[1,0,0]
	v_pk_fma_f32 v[88:89], v[106:107], s[60:61], v[80:81] op_sel_hi:[1,0,1] neg_lo:[1,0,0] neg_hi:[1,0,0]
	s_and_saveexec_b64 s[26:27], vcc
	s_cbranch_execz .LBB0_412
	v_cmp_lt_i32_e64 s[18:19], -10, v126
	v_cmp_lt_i32_e64 s[20:21], -9, v126
	v_cmp_lt_i32_e64 s[16:17], -11, v126
	s_or_b64 s[18:19], s[20:21], s[18:19]
	v_cmp_lt_i32_e64 s[14:15], -12, v126
	s_or_b64 s[16:17], s[18:19], s[16:17]
	v_cmp_lt_i32_e64 s[12:13], -13, v126
	s_or_b64 s[14:15], s[16:17], s[14:15]
	v_cmp_lt_i32_e64 s[10:11], -14, v126
	s_or_b64 s[12:13], s[14:15], s[12:13]
	v_cmp_lt_i32_e64 s[8:9], -15, v126
	s_or_b64 s[10:11], s[12:13], s[10:11]
	v_cmp_lt_i32_e32 vcc, -16, v126
	s_or_b64 s[8:9], s[10:11], s[8:9]
	s_or_b64 vcc, s[8:9], vcc
	v_cndmask_b32_e64 v81, v211, v81, s[20:21]
	v_cndmask_b32_e64 v80, v211, v80, s[18:19]
	v_cndmask_b32_e64 v79, v211, v79, s[16:17]
	v_cndmask_b32_e64 v78, v211, v78, s[14:15]
	v_cndmask_b32_e64 v77, v211, v77, s[12:13]
	v_cndmask_b32_e64 v76, v211, v76, s[10:11]
	v_cndmask_b32_e64 v3, v211, v3, s[8:9]
	v_cndmask_b32_e32 v2, v211, v2, vcc
	v_cndmask_b32_e32 v82, 0, v82, vcc
	v_cndmask_b32_e64 v83, 0, v83, s[8:9]
	v_cndmask_b32_e64 v84, 0, v84, s[10:11]
	v_cndmask_b32_e64 v85, 0, v85, s[12:13]
	v_cndmask_b32_e64 v86, 0, v86, s[14:15]
	v_cndmask_b32_e64 v87, 0, v87, s[16:17]
	v_cndmask_b32_e64 v88, 0, v88, s[18:19]
	v_cndmask_b32_e64 v89, 0, v89, s[20:21]
	s_branch .LBB0_412
